# hand-written residual-GEMM epilogue: all residual loads issued up front with counted waits, saddr addressing, pipelined row reductions
# baseline (speedup 1.0000x reference)
;     __device__ __forceinline__ void operator()(const f32x4 (&acc)[2][2][4][2], const Unit& u, int wr, int wc, int fr, int fq, LAS unsigned char* lds, int tid, int ui, const Unit& nxt, bool has_next) const {
;         const int row0 = u.pm * 256 + wr * 64 + fr, col0 = u.pn * 256 + wc * 32 + 8 * fq;
;         f32x4 bv[2][2];
; #pragma unroll
;         for (int bj = 0; bj < 2; ++bj)
; #pragma unroll
;             for (int n = 0; n < 2; ++n) bv[bj][n] = bias ? *(const f32x4*)(bias + col0 + bj * 128 + 4 * n) : (f32x4){0.f, 0.f, 0.f, 0.f};
; #pragma unroll
;         for (int ai = 0; ai < 2; ++ai) {
;             u32x4 xr[4][2];
; #pragma unroll
;             for (int m = 0; m < 4; ++m)
; #pragma unroll
;                 for (int bj = 0; bj < 2; ++bj) xr[m][bj] = *(const u32x4*)(xb + (size_t)(row0 + ai * 128 + m * 16) * D + col0 + bj * 128);
; #pragma unroll
;             for (int m = 0; m < 4; ++m) {
;                 const int row = row0 + ai * 128 + m * 16; const size_t off = (size_t)row * D + col0;
;                 typedef float f32x2 __attribute__((ext_vector_type(2)));
;                 f32x2 sq2 = (f32x2){0.f, 0.f};
; #pragma unroll
;                 for (int bj = 0; bj < 2; ++bj) {
;                     f32x2 v[4];
;                     const u32x4 w0 = xr[m][bj];
; #pragma unroll
;                     for (int i = 0; i < 4; ++i) v[i] = (f32x2){__uint_as_float(w0[i] << 16), __uint_as_float(w0[i] & 0xffff0000u)};
;                     const f32x2 al2 = (f32x2){alpha, alpha};
;                     unsigned wv[4];
; #pragma unroll
;                     for (int i = 0; i < 4; ++i) {
;                         const f32x4 av = acc[ai][bj][m][i >> 1], bb = bv[bj][i >> 1];
;                         const f32x2 a2 = (i & 1) ? (f32x2){av.z, av.w} : (f32x2){av.x, av.y}, b2 = (i & 1) ? (f32x2){bb.z, bb.w} : (f32x2){bb.x, bb.y};
;                         v[i] = __builtin_elementwise_fma(a2, al2, v[i]) + b2;
;                         sq2 = __builtin_elementwise_fma(v[i], v[i], sq2);
;                         wv[i] = cvt_pk_bf16(v[i].x, v[i].y);
;                     }
;                     u32x4 w; w.x = wv[0]; w.y = wv[1]; w.z = wv[2]; w.w = wv[3];
;                     *(u32x4*)(xb + off + bj * 128) = w;
;                 }
;                 float sq = sq2.x + sq2.y;
;                 sq += __shfl_xor(sq, 16); sq += __shfl_xor(sq, 32);
.LBB0_204:
	v_lshl_add_u32 v200, s69, 8, v233
	v_lshlrev_b32_e32 v216, 11, v200
	v_lshlrev_b32_e32 v217, 6, v200
	v_lshl_add_u32 v216, v196, 1, v216
	v_cmp_lt_i32_e32 vcc, v230, v225
	s_lshl_b32 s72, s68, 4
	s_lshl_b32 s73, s62, 2
	v_cndmask_b32_e32 v220, v224, v230, vcc
	s_add_u32 s72, s72, s73
	v_lshlrev_b32_e32 v237, 2, v220
	v_cmp_lt_i32_e32 vcc, v231, v225
	s_add_u32 s72, s48, s72
	s_addc_u32 s73, s49, 0
	v_cndmask_b32_e32 v221, v224, v231, vcc
	v_lshlrev_b32_e32 v220, 2, v221
	s_mov_b64 s[76:77], s[82:83]
	global_load_dwordx4 v[144:147], v216, s[76:77]
	global_load_dwordx4 v[148:151], v216, s[76:77] offset:256
	s_add_u32 s76, s82, 0x8000
	s_addc_u32 s77, s83, 0
	global_load_dwordx4 v[152:155], v216, s[76:77]
	global_load_dwordx4 v[156:159], v216, s[76:77] offset:256
	s_add_u32 s76, s82, 0x10000
	s_addc_u32 s77, s83, 0
	global_load_dwordx4 v[160:163], v216, s[76:77]
	global_load_dwordx4 v[164:167], v216, s[76:77] offset:256
	s_add_u32 s76, s82, 0x18000
	s_addc_u32 s77, s83, 0
	global_load_dwordx4 v[168:171], v216, s[76:77]
	global_load_dwordx4 v[172:175], v216, s[76:77] offset:256
	s_add_u32 s76, s82, 0x40000
	s_addc_u32 s77, s83, 0
	global_load_dwordx4 v[196:199], v216, s[76:77]
	global_load_dwordx4 v[200:203], v216, s[76:77] offset:256
	s_add_u32 s76, s82, 0x48000
	s_addc_u32 s77, s83, 0
	global_load_dwordx4 v[204:207], v216, s[76:77]
	global_load_dwordx4 v[208:211], v216, s[76:77] offset:256
	s_add_u32 s76, s82, 0x50000
	s_addc_u32 s77, s83, 0
	global_load_dwordx4 v[240:243], v216, s[76:77]
	global_load_dwordx4 v[244:247], v216, s[76:77] offset:256
	s_waitcnt vmcnt(12)
	s_cmp_eq_u64 s[50:51], 0
	s_cbranch_scc1 .Lmy_epibar_resid
	s_barrier
.Lmy_epibar_resid:
	v_lshlrev_b32_e32 v212, 16, v144
	v_and_b32_e32 v213, 0xffff0000, v144
	v_pk_fma_f32 v[140:141], v[140:141], s[26:27], v[212:213]
	v_pk_add_f32 v[140:141], v[76:77], v[140:141]
	v_pk_mul_f32 v[248:249], v[140:141], v[140:141]
	v_cvt_pk_bf16_f32 v144, v140, v141
	v_lshlrev_b32_e32 v212, 16, v145
	v_and_b32_e32 v213, 0xffff0000, v145
	v_pk_fma_f32 v[142:143], v[142:143], s[26:27], v[212:213]
	v_pk_add_f32 v[142:143], v[78:79], v[142:143]
	v_pk_fma_f32 v[248:249], v[142:143], v[142:143], v[248:249]
	v_cvt_pk_bf16_f32 v145, v142, v143
	v_lshlrev_b32_e32 v212, 16, v146
	v_and_b32_e32 v213, 0xffff0000, v146
	v_pk_fma_f32 v[136:137], v[136:137], s[26:27], v[212:213]
	v_pk_add_f32 v[136:137], v[68:69], v[136:137]
	v_pk_fma_f32 v[248:249], v[136:137], v[136:137], v[248:249]
	v_cvt_pk_bf16_f32 v146, v136, v137
	v_lshlrev_b32_e32 v212, 16, v147
	v_and_b32_e32 v213, 0xffff0000, v147
	v_pk_fma_f32 v[138:139], v[138:139], s[26:27], v[212:213]
	v_pk_add_f32 v[138:139], v[70:71], v[138:139]
	v_pk_fma_f32 v[248:249], v[138:139], v[138:139], v[248:249]
	v_cvt_pk_bf16_f32 v147, v138, v139
	s_mov_b64 s[76:77], s[82:83]
	global_store_dwordx4 v216, v[144:147], s[76:77]
	v_lshlrev_b32_e32 v212, 16, v148
	v_and_b32_e32 v213, 0xffff0000, v148
	v_pk_fma_f32 v[132:133], v[132:133], s[26:27], v[212:213]
	v_pk_add_f32 v[132:133], v[72:73], v[132:133]
	v_pk_fma_f32 v[248:249], v[132:133], v[132:133], v[248:249]
	v_cvt_pk_bf16_f32 v148, v132, v133
	v_lshlrev_b32_e32 v212, 16, v149
	v_and_b32_e32 v213, 0xffff0000, v149
	v_pk_fma_f32 v[134:135], v[134:135], s[26:27], v[212:213]
	v_pk_add_f32 v[134:135], v[74:75], v[134:135]
	v_pk_fma_f32 v[248:249], v[134:135], v[134:135], v[248:249]
	v_cvt_pk_bf16_f32 v149, v134, v135
	v_lshlrev_b32_e32 v212, 16, v150
	v_and_b32_e32 v213, 0xffff0000, v150
	v_pk_fma_f32 v[128:129], v[128:129], s[26:27], v[212:213]
	v_pk_add_f32 v[128:129], v[64:65], v[128:129]
	v_pk_fma_f32 v[248:249], v[128:129], v[128:129], v[248:249]
	v_cvt_pk_bf16_f32 v150, v128, v129
	v_lshlrev_b32_e32 v212, 16, v151
	v_and_b32_e32 v213, 0xffff0000, v151
	v_pk_fma_f32 v[130:131], v[130:131], s[26:27], v[212:213]
	v_pk_add_f32 v[130:131], v[66:67], v[130:131]
	v_pk_fma_f32 v[248:249], v[130:131], v[130:131], v[248:249]
	v_cvt_pk_bf16_f32 v151, v130, v131
	global_store_dwordx4 v216, v[148:151], s[76:77] offset:256
	v_add_f32_e32 v238, v248, v249
	ds_bpermute_b32 v239, v237, v238
	s_add_u32 s76, s82, 0x58000
	s_addc_u32 s77, s83, 0
	global_load_dwordx4 v[140:143], v216, s[76:77]
	global_load_dwordx4 v[136:139], v216, s[76:77] offset:256
	s_waitcnt vmcnt(14)
	v_lshlrev_b32_e32 v212, 16, v152
	v_and_b32_e32 v213, 0xffff0000, v152
	v_pk_fma_f32 v[124:125], v[124:125], s[26:27], v[212:213]
	v_pk_add_f32 v[124:125], v[76:77], v[124:125]
	v_pk_mul_f32 v[248:249], v[124:125], v[124:125]
	v_cvt_pk_bf16_f32 v152, v124, v125
	v_lshlrev_b32_e32 v212, 16, v153
	v_and_b32_e32 v213, 0xffff0000, v153
	v_pk_fma_f32 v[126:127], v[126:127], s[26:27], v[212:213]
	v_pk_add_f32 v[126:127], v[78:79], v[126:127]
	v_pk_fma_f32 v[248:249], v[126:127], v[126:127], v[248:249]
	v_cvt_pk_bf16_f32 v153, v126, v127
	v_lshlrev_b32_e32 v212, 16, v154
	v_and_b32_e32 v213, 0xffff0000, v154
	v_pk_fma_f32 v[120:121], v[120:121], s[26:27], v[212:213]
	v_pk_add_f32 v[120:121], v[68:69], v[120:121]
	v_pk_fma_f32 v[248:249], v[120:121], v[120:121], v[248:249]
	v_cvt_pk_bf16_f32 v154, v120, v121
	v_lshlrev_b32_e32 v212, 16, v155
	v_and_b32_e32 v213, 0xffff0000, v155
	v_pk_fma_f32 v[122:123], v[122:123], s[26:27], v[212:213]
	v_pk_add_f32 v[122:123], v[70:71], v[122:123]
	v_pk_fma_f32 v[248:249], v[122:123], v[122:123], v[248:249]
	v_cvt_pk_bf16_f32 v155, v122, v123
	s_add_u32 s76, s82, 0x8000
	s_addc_u32 s77, s83, 0
	global_store_dwordx4 v216, v[152:155], s[76:77]
	s_waitcnt lgkmcnt(0)
; __device__ __forceinline__ unsigned cvt_pk_bf16(float lo, float hi) { unsigned r; asm volatile("v_cvt_pk_bf16_f32 %0, %1, %2" : "=v"(r) : "v"(lo), "v"(hi)); return r; }
;     __device__ __forceinline__ void operator()(const f32x4 (&acc)[2][2][4][2], const Unit& u, int wr, int wc, int fr, int fq, LAS unsigned char* lds, int tid, int ui, const Unit& nxt, bool has_next) const {
;     ...
;             for (int m = 0; m < 4; ++m) {
;                 const int row = row0 + ai * 128 + m * 16; const size_t off = (size_t)row * D + col0;
;                 typedef float f32x2 __attribute__((ext_vector_type(2)));
;                 f32x2 sq2 = (f32x2){0.f, 0.f};
; #pragma unroll
;                 for (int bj = 0; bj < 2; ++bj) {
;                     f32x2 v[4];
;                     const u32x4 w0 = xr[m][bj];
; #pragma unroll
;                     for (int i = 0; i < 4; ++i) v[i] = (f32x2){__uint_as_float(w0[i] << 16), __uint_as_float(w0[i] & 0xffff0000u)};
;                     const f32x2 al2 = (f32x2){alpha, alpha};
;                     unsigned wv[4];
; #pragma unroll
;                     for (int i = 0; i < 4; ++i) {
;                         const f32x4 av = acc[ai][bj][m][i >> 1], bb = bv[bj][i >> 1];
;                         const f32x2 a2 = (i & 1) ? (f32x2){av.z, av.w} : (f32x2){av.x, av.y}, b2 = (i & 1) ? (f32x2){bb.z, bb.w} : (f32x2){bb.x, bb.y};
;                         v[i] = __builtin_elementwise_fma(a2, al2, v[i]) + b2;
;                         sq2 = __builtin_elementwise_fma(v[i], v[i], sq2);
;                         wv[i] = cvt_pk_bf16(v[i].x, v[i].y);
;                     }
;                     u32x4 w; w.x = wv[0]; w.y = wv[1]; w.z = wv[2]; w.w = wv[3];
;                     *(u32x4*)(xb + off + bj * 128) = w;
;                 }
;                 float sq = sq2.x + sq2.y;
;                 sq += __shfl_xor(sq, 16); sq += __shfl_xor(sq, 32);
;                 if (fq == 0) ssp[(size_t)row * 16 + u.pn * 4 + wc] = sq;
	v_add_f32_e32 v238, v238, v239
	ds_bpermute_b32 v239, v220, v238
	v_lshlrev_b32_e32 v212, 16, v156
	v_and_b32_e32 v213, 0xffff0000, v156
	v_pk_fma_f32 v[116:117], v[116:117], s[26:27], v[212:213]
	v_pk_add_f32 v[116:117], v[72:73], v[116:117]
	v_pk_fma_f32 v[248:249], v[116:117], v[116:117], v[248:249]
	v_cvt_pk_bf16_f32 v156, v116, v117
	v_lshlrev_b32_e32 v212, 16, v157
	v_and_b32_e32 v213, 0xffff0000, v157
	v_pk_fma_f32 v[118:119], v[118:119], s[26:27], v[212:213]
	v_pk_add_f32 v[118:119], v[74:75], v[118:119]
	v_pk_fma_f32 v[248:249], v[118:119], v[118:119], v[248:249]
	v_cvt_pk_bf16_f32 v157, v118, v119
	v_lshlrev_b32_e32 v212, 16, v158
	v_and_b32_e32 v213, 0xffff0000, v158
	v_pk_fma_f32 v[112:113], v[112:113], s[26:27], v[212:213]
	v_pk_add_f32 v[112:113], v[64:65], v[112:113]
	v_pk_fma_f32 v[248:249], v[112:113], v[112:113], v[248:249]
	v_cvt_pk_bf16_f32 v158, v112, v113
	v_lshlrev_b32_e32 v212, 16, v159
	v_and_b32_e32 v213, 0xffff0000, v159
	v_pk_fma_f32 v[114:115], v[114:115], s[26:27], v[212:213]
	v_pk_add_f32 v[114:115], v[66:67], v[114:115]
	v_pk_fma_f32 v[248:249], v[114:115], v[114:115], v[248:249]
	v_cvt_pk_bf16_f32 v159, v114, v115
	global_store_dwordx4 v216, v[156:159], s[76:77] offset:256
	s_waitcnt lgkmcnt(0)
	v_add_f32_e32 v238, v238, v239
	s_mov_b64 s[74:75], s[72:73]
	s_and_saveexec_b64 s[4:5], s[38:39]
	global_store_dword v217, v238, s[74:75]
	s_mov_b64 exec, s[4:5]
	v_add_f32_e32 v214, v248, v249
	ds_bpermute_b32 v215, v237, v214
	s_waitcnt vmcnt(15)
	v_lshlrev_b32_e32 v212, 16, v160
	v_and_b32_e32 v213, 0xffff0000, v160
	v_pk_fma_f32 v[108:109], v[108:109], s[26:27], v[212:213]
	v_pk_add_f32 v[108:109], v[76:77], v[108:109]
	v_pk_mul_f32 v[248:249], v[108:109], v[108:109]
	v_cvt_pk_bf16_f32 v160, v108, v109
	v_lshlrev_b32_e32 v212, 16, v161
	v_and_b32_e32 v213, 0xffff0000, v161
	v_pk_fma_f32 v[110:111], v[110:111], s[26:27], v[212:213]
	v_pk_add_f32 v[110:111], v[78:79], v[110:111]
	v_pk_fma_f32 v[248:249], v[110:111], v[110:111], v[248:249]
	v_cvt_pk_bf16_f32 v161, v110, v111
	v_lshlrev_b32_e32 v212, 16, v162
	v_and_b32_e32 v213, 0xffff0000, v162
	v_pk_fma_f32 v[104:105], v[104:105], s[26:27], v[212:213]
	v_pk_add_f32 v[104:105], v[68:69], v[104:105]
	v_pk_fma_f32 v[248:249], v[104:105], v[104:105], v[248:249]
	v_cvt_pk_bf16_f32 v162, v104, v105
	v_lshlrev_b32_e32 v212, 16, v163
	v_and_b32_e32 v213, 0xffff0000, v163
	v_pk_fma_f32 v[106:107], v[106:107], s[26:27], v[212:213]
	v_pk_add_f32 v[106:107], v[70:71], v[106:107]
	v_pk_fma_f32 v[248:249], v[106:107], v[106:107], v[248:249]
	v_cvt_pk_bf16_f32 v163, v106, v107
	s_add_u32 s76, s82, 0x10000
	s_addc_u32 s77, s83, 0
	global_store_dwordx4 v216, v[160:163], s[76:77]
	s_waitcnt lgkmcnt(0)
	v_add_f32_e32 v214, v214, v215
	ds_bpermute_b32 v215, v220, v214
	v_lshlrev_b32_e32 v212, 16, v164
	v_and_b32_e32 v213, 0xffff0000, v164
	v_pk_fma_f32 v[100:101], v[100:101], s[26:27], v[212:213]
	v_pk_add_f32 v[100:101], v[72:73], v[100:101]
	v_pk_fma_f32 v[248:249], v[100:101], v[100:101], v[248:249]
	v_cvt_pk_bf16_f32 v164, v100, v101
	v_lshlrev_b32_e32 v212, 16, v165
	v_and_b32_e32 v213, 0xffff0000, v165
	v_pk_fma_f32 v[102:103], v[102:103], s[26:27], v[212:213]
	v_pk_add_f32 v[102:103], v[74:75], v[102:103]
	v_pk_fma_f32 v[248:249], v[102:103], v[102:103], v[248:249]
	v_cvt_pk_bf16_f32 v165, v102, v103
	v_lshlrev_b32_e32 v212, 16, v166
	v_and_b32_e32 v213, 0xffff0000, v166
	v_pk_fma_f32 v[96:97], v[96:97], s[26:27], v[212:213]
	v_pk_add_f32 v[96:97], v[64:65], v[96:97]
	v_pk_fma_f32 v[248:249], v[96:97], v[96:97], v[248:249]
	v_cvt_pk_bf16_f32 v166, v96, v97
	v_lshlrev_b32_e32 v212, 16, v167
	v_and_b32_e32 v213, 0xffff0000, v167
	v_pk_fma_f32 v[98:99], v[98:99], s[26:27], v[212:213]
	v_pk_add_f32 v[98:99], v[66:67], v[98:99]
	v_pk_fma_f32 v[248:249], v[98:99], v[98:99], v[248:249]
	v_cvt_pk_bf16_f32 v167, v98, v99
	global_store_dwordx4 v216, v[164:167], s[76:77] offset:256
	s_waitcnt lgkmcnt(0)
	v_add_f32_e32 v214, v214, v215
	s_add_u32 s74, s72, 0x400
	s_addc_u32 s75, s73, 0
	s_and_saveexec_b64 s[4:5], s[38:39]
	global_store_dword v217, v214, s[74:75]
	s_mov_b64 exec, s[4:5]
	v_add_f32_e32 v238, v248, v249
	ds_bpermute_b32 v239, v237, v238
	s_waitcnt vmcnt(16)
	v_lshlrev_b32_e32 v212, 16, v168
	v_and_b32_e32 v213, 0xffff0000, v168
	v_pk_fma_f32 v[92:93], v[92:93], s[26:27], v[212:213]
	v_pk_add_f32 v[92:93], v[76:77], v[92:93]
	v_pk_mul_f32 v[248:249], v[92:93], v[92:93]
	v_cvt_pk_bf16_f32 v168, v92, v93
	v_lshlrev_b32_e32 v212, 16, v169
	v_and_b32_e32 v213, 0xffff0000, v169
	v_pk_fma_f32 v[94:95], v[94:95], s[26:27], v[212:213]
	v_pk_add_f32 v[94:95], v[78:79], v[94:95]
	v_pk_fma_f32 v[248:249], v[94:95], v[94:95], v[248:249]
	v_cvt_pk_bf16_f32 v169, v94, v95
	v_lshlrev_b32_e32 v212, 16, v170
	v_and_b32_e32 v213, 0xffff0000, v170
	v_pk_fma_f32 v[88:89], v[88:89], s[26:27], v[212:213]
	v_pk_add_f32 v[88:89], v[68:69], v[88:89]
	v_pk_fma_f32 v[248:249], v[88:89], v[88:89], v[248:249]
	v_cvt_pk_bf16_f32 v170, v88, v89
	v_lshlrev_b32_e32 v212, 16, v171
	v_and_b32_e32 v213, 0xffff0000, v171
	v_pk_fma_f32 v[90:91], v[90:91], s[26:27], v[212:213]
	v_pk_add_f32 v[90:91], v[70:71], v[90:91]
	v_pk_fma_f32 v[248:249], v[90:91], v[90:91], v[248:249]
	v_cvt_pk_bf16_f32 v171, v90, v91
	s_add_u32 s76, s82, 0x18000
	s_addc_u32 s77, s83, 0
	global_store_dwordx4 v216, v[168:171], s[76:77]
	s_waitcnt lgkmcnt(0)
; __device__ __forceinline__ unsigned cvt_pk_bf16(float lo, float hi) { unsigned r; asm volatile("v_cvt_pk_bf16_f32 %0, %1, %2" : "=v"(r) : "v"(lo), "v"(hi)); return r; }
;     __device__ __forceinline__ void operator()(const f32x4 (&acc)[2][2][4][2], const Unit& u, int wr, int wc, int fr, int fq, LAS unsigned char* lds, int tid, int ui, const Unit& nxt, bool has_next) const {
;     ...
;             for (int m = 0; m < 4; ++m) {
;                 const int row = row0 + ai * 128 + m * 16; const size_t off = (size_t)row * D + col0;
;                 typedef float f32x2 __attribute__((ext_vector_type(2)));
;                 f32x2 sq2 = (f32x2){0.f, 0.f};
; #pragma unroll
;                 for (int bj = 0; bj < 2; ++bj) {
;                     f32x2 v[4];
;                     const u32x4 w0 = xr[m][bj];
; #pragma unroll
;                     for (int i = 0; i < 4; ++i) v[i] = (f32x2){__uint_as_float(w0[i] << 16), __uint_as_float(w0[i] & 0xffff0000u)};
;                     const f32x2 al2 = (f32x2){alpha, alpha};
;                     unsigned wv[4];
; #pragma unroll
;                     for (int i = 0; i < 4; ++i) {
;                         const f32x4 av = acc[ai][bj][m][i >> 1], bb = bv[bj][i >> 1];
;                         const f32x2 a2 = (i & 1) ? (f32x2){av.z, av.w} : (f32x2){av.x, av.y}, b2 = (i & 1) ? (f32x2){bb.z, bb.w} : (f32x2){bb.x, bb.y};
;                         v[i] = __builtin_elementwise_fma(a2, al2, v[i]) + b2;
;                         sq2 = __builtin_elementwise_fma(v[i], v[i], sq2);
;                         wv[i] = cvt_pk_bf16(v[i].x, v[i].y);
;                     }
;                     u32x4 w; w.x = wv[0]; w.y = wv[1]; w.z = wv[2]; w.w = wv[3];
;                     *(u32x4*)(xb + off + bj * 128) = w;
;                 }
;                 float sq = sq2.x + sq2.y;
;                 sq += __shfl_xor(sq, 16); sq += __shfl_xor(sq, 32);
;                 if (fq == 0) ssp[(size_t)row * 16 + u.pn * 4 + wc] = sq;
	v_add_f32_e32 v238, v238, v239
	ds_bpermute_b32 v239, v220, v238
	v_lshlrev_b32_e32 v212, 16, v172
	v_and_b32_e32 v213, 0xffff0000, v172
	v_pk_fma_f32 v[84:85], v[84:85], s[26:27], v[212:213]
	v_pk_add_f32 v[84:85], v[72:73], v[84:85]
	v_pk_fma_f32 v[248:249], v[84:85], v[84:85], v[248:249]
	v_cvt_pk_bf16_f32 v172, v84, v85
	v_lshlrev_b32_e32 v212, 16, v173
	v_and_b32_e32 v213, 0xffff0000, v173
	v_pk_fma_f32 v[86:87], v[86:87], s[26:27], v[212:213]
	v_pk_add_f32 v[86:87], v[74:75], v[86:87]
	v_pk_fma_f32 v[248:249], v[86:87], v[86:87], v[248:249]
	v_cvt_pk_bf16_f32 v173, v86, v87
	v_lshlrev_b32_e32 v212, 16, v174
	v_and_b32_e32 v213, 0xffff0000, v174
	v_pk_fma_f32 v[80:81], v[80:81], s[26:27], v[212:213]
	v_pk_add_f32 v[80:81], v[64:65], v[80:81]
	v_pk_fma_f32 v[248:249], v[80:81], v[80:81], v[248:249]
	v_cvt_pk_bf16_f32 v174, v80, v81
	v_lshlrev_b32_e32 v212, 16, v175
	v_and_b32_e32 v213, 0xffff0000, v175
	v_pk_fma_f32 v[82:83], v[82:83], s[26:27], v[212:213]
	v_pk_add_f32 v[82:83], v[66:67], v[82:83]
	v_pk_fma_f32 v[248:249], v[82:83], v[82:83], v[248:249]
	v_cvt_pk_bf16_f32 v175, v82, v83
	global_store_dwordx4 v216, v[172:175], s[76:77] offset:256
	s_waitcnt lgkmcnt(0)
	v_add_f32_e32 v238, v238, v239
	s_add_u32 s74, s72, 0x800
	s_addc_u32 s75, s73, 0
	s_and_saveexec_b64 s[4:5], s[38:39]
	global_store_dword v217, v238, s[74:75]
	s_mov_b64 exec, s[4:5]
	v_add_f32_e32 v214, v248, v249
	ds_bpermute_b32 v215, v237, v214
	s_waitcnt vmcnt(17)
	v_lshlrev_b32_e32 v212, 16, v196
	v_and_b32_e32 v213, 0xffff0000, v196
	v_pk_fma_f32 v[60:61], v[60:61], s[26:27], v[212:213]
	v_pk_add_f32 v[60:61], v[76:77], v[60:61]
	v_pk_mul_f32 v[248:249], v[60:61], v[60:61]
	v_cvt_pk_bf16_f32 v196, v60, v61
	v_lshlrev_b32_e32 v212, 16, v197
	v_and_b32_e32 v213, 0xffff0000, v197
	v_pk_fma_f32 v[62:63], v[62:63], s[26:27], v[212:213]
	v_pk_add_f32 v[62:63], v[78:79], v[62:63]
	v_pk_fma_f32 v[248:249], v[62:63], v[62:63], v[248:249]
	v_cvt_pk_bf16_f32 v197, v62, v63
	v_lshlrev_b32_e32 v212, 16, v198
	v_and_b32_e32 v213, 0xffff0000, v198
	v_pk_fma_f32 v[56:57], v[56:57], s[26:27], v[212:213]
	v_pk_add_f32 v[56:57], v[68:69], v[56:57]
	v_pk_fma_f32 v[248:249], v[56:57], v[56:57], v[248:249]
	v_cvt_pk_bf16_f32 v198, v56, v57
	v_lshlrev_b32_e32 v212, 16, v199
	v_and_b32_e32 v213, 0xffff0000, v199
	v_pk_fma_f32 v[58:59], v[58:59], s[26:27], v[212:213]
	v_pk_add_f32 v[58:59], v[70:71], v[58:59]
	v_pk_fma_f32 v[248:249], v[58:59], v[58:59], v[248:249]
	v_cvt_pk_bf16_f32 v199, v58, v59
	s_add_u32 s76, s82, 0x40000
	s_addc_u32 s77, s83, 0
	global_store_dwordx4 v216, v[196:199], s[76:77]
	s_waitcnt lgkmcnt(0)
	v_add_f32_e32 v214, v214, v215
	ds_bpermute_b32 v215, v220, v214
	v_lshlrev_b32_e32 v212, 16, v200
	v_and_b32_e32 v213, 0xffff0000, v200
	v_pk_fma_f32 v[52:53], v[52:53], s[26:27], v[212:213]
	v_pk_add_f32 v[52:53], v[72:73], v[52:53]
	v_pk_fma_f32 v[248:249], v[52:53], v[52:53], v[248:249]
	v_cvt_pk_bf16_f32 v200, v52, v53
	v_lshlrev_b32_e32 v212, 16, v201
	v_and_b32_e32 v213, 0xffff0000, v201
	v_pk_fma_f32 v[54:55], v[54:55], s[26:27], v[212:213]
	v_pk_add_f32 v[54:55], v[74:75], v[54:55]
	v_pk_fma_f32 v[248:249], v[54:55], v[54:55], v[248:249]
	v_cvt_pk_bf16_f32 v201, v54, v55
	v_lshlrev_b32_e32 v212, 16, v202
	v_and_b32_e32 v213, 0xffff0000, v202
	v_pk_fma_f32 v[48:49], v[48:49], s[26:27], v[212:213]
	v_pk_add_f32 v[48:49], v[64:65], v[48:49]
	v_pk_fma_f32 v[248:249], v[48:49], v[48:49], v[248:249]
	v_cvt_pk_bf16_f32 v202, v48, v49
	v_lshlrev_b32_e32 v212, 16, v203
	v_and_b32_e32 v213, 0xffff0000, v203
	v_pk_fma_f32 v[50:51], v[50:51], s[26:27], v[212:213]
	v_pk_add_f32 v[50:51], v[66:67], v[50:51]
	v_pk_fma_f32 v[248:249], v[50:51], v[50:51], v[248:249]
	v_cvt_pk_bf16_f32 v203, v50, v51
	global_store_dwordx4 v216, v[200:203], s[76:77] offset:256
	s_waitcnt lgkmcnt(0)
	v_add_f32_e32 v214, v214, v215
	s_add_u32 s74, s72, 0xc00
	s_addc_u32 s75, s73, 0
	s_and_saveexec_b64 s[4:5], s[38:39]
	global_store_dword v217, v214, s[74:75]
	s_mov_b64 exec, s[4:5]
	v_add_f32_e32 v238, v248, v249
	ds_bpermute_b32 v239, v237, v238
	s_waitcnt vmcnt(18)
	v_lshlrev_b32_e32 v212, 16, v204
	v_and_b32_e32 v213, 0xffff0000, v204
	v_pk_fma_f32 v[44:45], v[44:45], s[26:27], v[212:213]
	v_pk_add_f32 v[44:45], v[76:77], v[44:45]
	v_pk_mul_f32 v[248:249], v[44:45], v[44:45]
	v_cvt_pk_bf16_f32 v204, v44, v45
	v_lshlrev_b32_e32 v212, 16, v205
	v_and_b32_e32 v213, 0xffff0000, v205
	v_pk_fma_f32 v[46:47], v[46:47], s[26:27], v[212:213]
	v_pk_add_f32 v[46:47], v[78:79], v[46:47]
	v_pk_fma_f32 v[248:249], v[46:47], v[46:47], v[248:249]
	v_cvt_pk_bf16_f32 v205, v46, v47
	v_lshlrev_b32_e32 v212, 16, v206
	v_and_b32_e32 v213, 0xffff0000, v206
	v_pk_fma_f32 v[40:41], v[40:41], s[26:27], v[212:213]
	v_pk_add_f32 v[40:41], v[68:69], v[40:41]
	v_pk_fma_f32 v[248:249], v[40:41], v[40:41], v[248:249]
	v_cvt_pk_bf16_f32 v206, v40, v41
	v_lshlrev_b32_e32 v212, 16, v207
	v_and_b32_e32 v213, 0xffff0000, v207
	v_pk_fma_f32 v[42:43], v[42:43], s[26:27], v[212:213]
	v_pk_add_f32 v[42:43], v[70:71], v[42:43]
	v_pk_fma_f32 v[248:249], v[42:43], v[42:43], v[248:249]
	v_cvt_pk_bf16_f32 v207, v42, v43
	s_add_u32 s76, s82, 0x48000
	s_addc_u32 s77, s83, 0
	global_store_dwordx4 v216, v[204:207], s[76:77]
	s_waitcnt lgkmcnt(0)
; __device__ __forceinline__ unsigned cvt_pk_bf16(float lo, float hi) { unsigned r; asm volatile("v_cvt_pk_bf16_f32 %0, %1, %2" : "=v"(r) : "v"(lo), "v"(hi)); return r; }
;     __device__ __forceinline__ void operator()(const f32x4 (&acc)[2][2][4][2], const Unit& u, int wr, int wc, int fr, int fq, LAS unsigned char* lds, int tid, int ui, const Unit& nxt, bool has_next) const {
;     ...
;             for (int m = 0; m < 4; ++m) {
;                 const int row = row0 + ai * 128 + m * 16; const size_t off = (size_t)row * D + col0;
;                 typedef float f32x2 __attribute__((ext_vector_type(2)));
;                 f32x2 sq2 = (f32x2){0.f, 0.f};
; #pragma unroll
;                 for (int bj = 0; bj < 2; ++bj) {
;                     f32x2 v[4];
;                     const u32x4 w0 = xr[m][bj];
; #pragma unroll
;                     for (int i = 0; i < 4; ++i) v[i] = (f32x2){__uint_as_float(w0[i] << 16), __uint_as_float(w0[i] & 0xffff0000u)};
;                     const f32x2 al2 = (f32x2){alpha, alpha};
;                     unsigned wv[4];
; #pragma unroll
;                     for (int i = 0; i < 4; ++i) {
;                         const f32x4 av = acc[ai][bj][m][i >> 1], bb = bv[bj][i >> 1];
;                         const f32x2 a2 = (i & 1) ? (f32x2){av.z, av.w} : (f32x2){av.x, av.y}, b2 = (i & 1) ? (f32x2){bb.z, bb.w} : (f32x2){bb.x, bb.y};
;                         v[i] = __builtin_elementwise_fma(a2, al2, v[i]) + b2;
;                         sq2 = __builtin_elementwise_fma(v[i], v[i], sq2);
;                         wv[i] = cvt_pk_bf16(v[i].x, v[i].y);
;                     }
;                     u32x4 w; w.x = wv[0]; w.y = wv[1]; w.z = wv[2]; w.w = wv[3];
;                     *(u32x4*)(xb + off + bj * 128) = w;
;                 }
;                 float sq = sq2.x + sq2.y;
;                 sq += __shfl_xor(sq, 16); sq += __shfl_xor(sq, 32);
;                 if (fq == 0) ssp[(size_t)row * 16 + u.pn * 4 + wc] = sq;
;             }
;             asm volatile("" ::: "memory");
;         }
	v_add_f32_e32 v238, v238, v239
	ds_bpermute_b32 v239, v220, v238
	v_lshlrev_b32_e32 v212, 16, v208
	v_and_b32_e32 v213, 0xffff0000, v208
	v_pk_fma_f32 v[36:37], v[36:37], s[26:27], v[212:213]
	v_pk_add_f32 v[36:37], v[72:73], v[36:37]
	v_pk_fma_f32 v[248:249], v[36:37], v[36:37], v[248:249]
	v_cvt_pk_bf16_f32 v208, v36, v37
	v_lshlrev_b32_e32 v212, 16, v209
	v_and_b32_e32 v213, 0xffff0000, v209
	v_pk_fma_f32 v[38:39], v[38:39], s[26:27], v[212:213]
	v_pk_add_f32 v[38:39], v[74:75], v[38:39]
	v_pk_fma_f32 v[248:249], v[38:39], v[38:39], v[248:249]
	v_cvt_pk_bf16_f32 v209, v38, v39
	v_lshlrev_b32_e32 v212, 16, v210
	v_and_b32_e32 v213, 0xffff0000, v210
	v_pk_fma_f32 v[32:33], v[32:33], s[26:27], v[212:213]
	v_pk_add_f32 v[32:33], v[64:65], v[32:33]
	v_pk_fma_f32 v[248:249], v[32:33], v[32:33], v[248:249]
	v_cvt_pk_bf16_f32 v210, v32, v33
	v_lshlrev_b32_e32 v212, 16, v211
	v_and_b32_e32 v213, 0xffff0000, v211
	v_pk_fma_f32 v[34:35], v[34:35], s[26:27], v[212:213]
	v_pk_add_f32 v[34:35], v[66:67], v[34:35]
	v_pk_fma_f32 v[248:249], v[34:35], v[34:35], v[248:249]
	v_cvt_pk_bf16_f32 v211, v34, v35
	global_store_dwordx4 v216, v[208:211], s[76:77] offset:256
	s_waitcnt lgkmcnt(0)
	v_add_f32_e32 v238, v238, v239
	s_add_u32 s74, s72, 0x2000
	s_addc_u32 s75, s73, 0
	s_and_saveexec_b64 s[4:5], s[38:39]
	global_store_dword v217, v238, s[74:75]
	s_mov_b64 exec, s[4:5]
	v_add_f32_e32 v214, v248, v249
	ds_bpermute_b32 v215, v237, v214
	s_waitcnt vmcnt(19)
	v_lshlrev_b32_e32 v212, 16, v240
	v_and_b32_e32 v213, 0xffff0000, v240
	v_pk_fma_f32 v[28:29], v[28:29], s[26:27], v[212:213]
	v_pk_add_f32 v[28:29], v[76:77], v[28:29]
	v_pk_mul_f32 v[248:249], v[28:29], v[28:29]
	v_cvt_pk_bf16_f32 v240, v28, v29
	v_lshlrev_b32_e32 v212, 16, v241
	v_and_b32_e32 v213, 0xffff0000, v241
	v_pk_fma_f32 v[30:31], v[30:31], s[26:27], v[212:213]
	v_pk_add_f32 v[30:31], v[78:79], v[30:31]
	v_pk_fma_f32 v[248:249], v[30:31], v[30:31], v[248:249]
	v_cvt_pk_bf16_f32 v241, v30, v31
	v_lshlrev_b32_e32 v212, 16, v242
	v_and_b32_e32 v213, 0xffff0000, v242
	v_pk_fma_f32 v[24:25], v[24:25], s[26:27], v[212:213]
	v_pk_add_f32 v[24:25], v[68:69], v[24:25]
	v_pk_fma_f32 v[248:249], v[24:25], v[24:25], v[248:249]
	v_cvt_pk_bf16_f32 v242, v24, v25
	v_lshlrev_b32_e32 v212, 16, v243
	v_and_b32_e32 v213, 0xffff0000, v243
	v_pk_fma_f32 v[26:27], v[26:27], s[26:27], v[212:213]
	v_pk_add_f32 v[26:27], v[70:71], v[26:27]
	v_pk_fma_f32 v[248:249], v[26:27], v[26:27], v[248:249]
	v_cvt_pk_bf16_f32 v243, v26, v27
	s_add_u32 s76, s82, 0x50000
	s_addc_u32 s77, s83, 0
	global_store_dwordx4 v216, v[240:243], s[76:77]
	s_waitcnt lgkmcnt(0)
	v_add_f32_e32 v214, v214, v215
	ds_bpermute_b32 v215, v220, v214
	v_lshlrev_b32_e32 v212, 16, v244
	v_and_b32_e32 v213, 0xffff0000, v244
	v_pk_fma_f32 v[20:21], v[20:21], s[26:27], v[212:213]
	v_pk_add_f32 v[20:21], v[72:73], v[20:21]
	v_pk_fma_f32 v[248:249], v[20:21], v[20:21], v[248:249]
	v_cvt_pk_bf16_f32 v244, v20, v21
	v_lshlrev_b32_e32 v212, 16, v245
	v_and_b32_e32 v213, 0xffff0000, v245
	v_pk_fma_f32 v[22:23], v[22:23], s[26:27], v[212:213]
	v_pk_add_f32 v[22:23], v[74:75], v[22:23]
	v_pk_fma_f32 v[248:249], v[22:23], v[22:23], v[248:249]
	v_cvt_pk_bf16_f32 v245, v22, v23
	v_lshlrev_b32_e32 v212, 16, v246
	v_and_b32_e32 v213, 0xffff0000, v246
	v_pk_fma_f32 v[16:17], v[16:17], s[26:27], v[212:213]
	v_pk_add_f32 v[16:17], v[64:65], v[16:17]
	v_pk_fma_f32 v[248:249], v[16:17], v[16:17], v[248:249]
	v_cvt_pk_bf16_f32 v246, v16, v17
	v_lshlrev_b32_e32 v212, 16, v247
	v_and_b32_e32 v213, 0xffff0000, v247
	v_pk_fma_f32 v[18:19], v[18:19], s[26:27], v[212:213]
	v_pk_add_f32 v[18:19], v[66:67], v[18:19]
	v_pk_fma_f32 v[248:249], v[18:19], v[18:19], v[248:249]
	v_cvt_pk_bf16_f32 v247, v18, v19
	global_store_dwordx4 v216, v[244:247], s[76:77] offset:256
	s_waitcnt lgkmcnt(0)
	v_add_f32_e32 v214, v214, v215
	s_add_u32 s74, s72, 0x2400
	s_addc_u32 s75, s73, 0
	s_and_saveexec_b64 s[4:5], s[38:39]
	global_store_dword v217, v214, s[74:75]
	s_mov_b64 exec, s[4:5]
	v_add_f32_e32 v238, v248, v249
	ds_bpermute_b32 v239, v237, v238
	s_waitcnt vmcnt(18)
	v_lshlrev_b32_e32 v212, 16, v140
	v_and_b32_e32 v213, 0xffff0000, v140
	v_pk_fma_f32 v[12:13], v[12:13], s[26:27], v[212:213]
	v_pk_add_f32 v[12:13], v[76:77], v[12:13]
	v_pk_mul_f32 v[248:249], v[12:13], v[12:13]
	v_cvt_pk_bf16_f32 v140, v12, v13
	v_lshlrev_b32_e32 v212, 16, v141
	v_and_b32_e32 v213, 0xffff0000, v141
	v_pk_fma_f32 v[14:15], v[14:15], s[26:27], v[212:213]
	v_pk_add_f32 v[14:15], v[78:79], v[14:15]
	v_pk_fma_f32 v[248:249], v[14:15], v[14:15], v[248:249]
	v_cvt_pk_bf16_f32 v141, v14, v15
	v_lshlrev_b32_e32 v212, 16, v142
	v_and_b32_e32 v213, 0xffff0000, v142
	v_pk_fma_f32 v[8:9], v[8:9], s[26:27], v[212:213]
	v_pk_add_f32 v[8:9], v[68:69], v[8:9]
	v_pk_fma_f32 v[248:249], v[8:9], v[8:9], v[248:249]
	v_cvt_pk_bf16_f32 v142, v8, v9
	v_lshlrev_b32_e32 v212, 16, v143
	v_and_b32_e32 v213, 0xffff0000, v143
	v_pk_fma_f32 v[10:11], v[10:11], s[26:27], v[212:213]
	v_pk_add_f32 v[10:11], v[70:71], v[10:11]
	v_pk_fma_f32 v[248:249], v[10:11], v[10:11], v[248:249]
	v_cvt_pk_bf16_f32 v143, v10, v11
	s_add_u32 s76, s82, 0x58000
	s_addc_u32 s77, s83, 0
	global_store_dwordx4 v216, v[140:143], s[76:77]
	s_waitcnt lgkmcnt(0)
	v_add_f32_e32 v238, v238, v239
	ds_bpermute_b32 v239, v220, v238
	v_lshlrev_b32_e32 v212, 16, v136
	v_and_b32_e32 v213, 0xffff0000, v136
	v_pk_fma_f32 v[4:5], v[4:5], s[26:27], v[212:213]
	v_pk_add_f32 v[4:5], v[72:73], v[4:5]
	v_pk_fma_f32 v[248:249], v[4:5], v[4:5], v[248:249]
	v_cvt_pk_bf16_f32 v136, v4, v5
	v_lshlrev_b32_e32 v212, 16, v137
	v_and_b32_e32 v213, 0xffff0000, v137
	v_pk_fma_f32 v[6:7], v[6:7], s[26:27], v[212:213]
	v_pk_add_f32 v[6:7], v[74:75], v[6:7]
	v_pk_fma_f32 v[248:249], v[6:7], v[6:7], v[248:249]
	v_cvt_pk_bf16_f32 v137, v6, v7
	v_lshlrev_b32_e32 v212, 16, v138
	v_and_b32_e32 v213, 0xffff0000, v138
	v_pk_fma_f32 v[0:1], v[0:1], s[26:27], v[212:213]
	v_pk_add_f32 v[0:1], v[64:65], v[0:1]
	v_pk_fma_f32 v[248:249], v[0:1], v[0:1], v[248:249]
	v_cvt_pk_bf16_f32 v138, v0, v1
	v_lshlrev_b32_e32 v212, 16, v139
	v_and_b32_e32 v213, 0xffff0000, v139
	v_pk_fma_f32 v[2:3], v[2:3], s[26:27], v[212:213]
	v_pk_add_f32 v[2:3], v[66:67], v[2:3]
	v_pk_fma_f32 v[248:249], v[2:3], v[2:3], v[248:249]
	v_cvt_pk_bf16_f32 v139, v2, v3
	global_store_dwordx4 v216, v[136:139], s[76:77] offset:256
	s_waitcnt lgkmcnt(0)
	v_add_f32_e32 v238, v238, v239
	s_add_u32 s74, s72, 0x2800
	s_addc_u32 s75, s73, 0
	s_and_saveexec_b64 s[4:5], s[38:39]
	global_store_dword v217, v238, s[74:75]
	s_mov_b64 exec, s[4:5]
	v_add_f32_e32 v214, v248, v249
	ds_bpermute_b32 v215, v237, v214
	s_waitcnt lgkmcnt(0)
	v_add_f32_e32 v214, v214, v215
	ds_bpermute_b32 v215, v220, v214
	s_waitcnt lgkmcnt(0)
	v_add_f32_e32 v214, v214, v215
	s_add_u32 s74, s72, 0x2c00
	s_addc_u32 s75, s73, 0
	s_and_saveexec_b64 s[4:5], s[38:39]
	global_store_dword v217, v214, s[74:75]
	s_mov_b64 exec, s[4:5]
	s_and_b64 vcc, exec, s[40:41]
	s_mov_b64 s[4:5], -1
	s_cbranch_vccnz .LBB0_181
; #define PG8_BAR __builtin_amdgcn_s_barrier()
; template <class Epi, class Sched, bool ALIGN_EPI = false, bool SP2 = false>
; __device__ __forceinline__ void gemm_phase(PG8_LAS unsigned char* lds, const Gemm g, const Sched& S, const Epi& E) {
;     ...
;         if (!has_next) break;
; #pragma unroll
;         for (int a = 0; a < 2; ++a)
; #pragma unroll
;             for (int b = 0; b < 2; ++b)
; #pragma unroll
;                 for (int m = 0; m < 4; ++m)
; #pragma unroll
;                     for (int n = 0; n < 2; ++n) acc[a][b][m][n] = (f32x4){0.f, 0.f, 0.f, 0.f};
;         cur = nxt; cA = nA; cB = nB; ++ui;
;         if constexpr (ALIGN_EPI) { if (wr == 1) PG8_BAR; }
	s_andn2_b64 vcc, exec, s[46:47]
	s_cbranch_vccnz .LBB0_180
	s_barrier
	s_branch .LBB0_180
